# P3 qknorm: 16 k-gain vector loads hoisted to token-loop top (no per-step load+vmcnt(0) waits)
# speedup vs baseline: 1.0104x; 1.0065x over previous
.LBB0_275:
	v_lshl_add_u64 v[6:7], s[96:97], 0, v[72:73]
	v_lshl_add_u64 v[2:3], s[96:97], 0, v[68:69]
	v_add_co_u32_e32 v6, vcc, 0x11000000, v6
	s_mov_b64 s[20:21], s[62:63]
	s_mov_b64 s[18:19], s[76:77]
	v_lshl_add_u64 v[186:187], s[76:77], 0, v[80:81]
	global_load_dwordx4 v[190:193], v[186:187], off
	global_load_dwordx4 v[194:197], v[186:187], off offset:16
	global_load_dwordx4 v[198:201], v[186:187], off offset:32
	global_load_dwordx4 v[202:205], v[186:187], off offset:48
	global_load_dwordx4 v[206:209], v[186:187], off offset:64
	global_load_dwordx4 v[210:213], v[186:187], off offset:80
	global_load_dwordx4 v[214:217], v[186:187], off offset:96
	global_load_dwordx4 v[218:221], v[186:187], off offset:112
	global_load_dwordx4 v[222:225], v[186:187], off offset:128
	global_load_dwordx4 v[226:229], v[186:187], off offset:144
	global_load_dwordx4 v[230:233], v[186:187], off offset:160
	global_load_dwordx4 v[234:237], v[186:187], off offset:176
	global_load_dwordx4 v[238:241], v[186:187], off offset:192
	global_load_dwordx4 v[242:245], v[186:187], off offset:208
	global_load_dwordx4 v[246:249], v[186:187], off offset:224
	global_load_dwordx4 v[250:253], v[186:187], off offset:240
	v_lshl_add_u64 v[4:5], v[2:3], 0, s[12:13]
	v_addc_co_u32_e32 v7, vcc, 0, v7, vcc
	global_load_dwordx4 v[48:51], v[4:5], off offset:32
	global_load_dwordx4 v[52:55], v[4:5], off offset:48
	global_load_dwordx4 v[56:59], v[6:7], off
	global_load_dwordx4 v[86:89], v[4:5], off offset:16
	v_add_co_u32_e32 v84, vcc, 0x1e000000, v2
	v_lshl_add_u64 v[4:5], s[96:97], 0, v[74:75]
	s_nop 0
	v_addc_co_u32_e32 v85, vcc, 0, v3, vcc
	global_load_dwordx4 v[90:93], v[84:85], off
	v_add_co_u32_e32 v44, vcc, s28, v4
	v_lshl_add_u64 v[42:43], s[96:97], 0, v[66:67]
	s_nop 0
	v_addc_co_u32_e32 v45, vcc, 0, v5, vcc
	v_add_co_u32_e32 v82, vcc, s30, v42
	v_lshl_add_u64 v[2:3], s[96:97], 0, v[70:71]
	s_nop 0
	v_addc_co_u32_e32 v83, vcc, 0, v43, vcc
	v_add_co_u32_e32 v100, vcc, s29, v2
	s_and_b32 s33, s26, 0x7ffe0
	s_nop 0
	v_addc_co_u32_e32 v101, vcc, 0, v3, vcc
	global_load_dwordx4 v[34:37], v[100:101], off
	global_load_dwordx4 v[38:41], v[100:101], off offset:64
	s_lshl_b32 s33, s33, 2
	s_add_u32 s34, s22, s33
	v_mov_b32_e32 v8, v62
	s_addc_u32 s35, s23, 0
	s_add_u32 s38, s24, s33
	v_lshl_add_u64 v[46:47], v[42:43], 0, s[14:15]
	s_addc_u32 s39, s25, 0
	global_load_dwordx4 v[30:33], v[6:7], off offset:1024
	global_load_dwordx4 v[26:29], v[44:45], off offset:2048
	global_load_dwordx4 v[18:21], v[46:47], off offset:48
	global_load_dwordx4 v[22:25], v[46:47], off offset:32
	global_load_dwordx4 v[10:13], v8, s[34:35]
	global_load_dwordx4 v[2:5], v8, s[34:35] offset:16
	global_load_dwordx4 v[14:17], v8, s[38:39]
	s_nop 0
	global_load_dwordx4 v[6:9], v8, s[38:39] offset:16
	v_lshl_add_u64 v[42:43], v[42:43], 0, s[16:17]
	v_lshl_add_u64 v[142:143], s[20:21], 0, v[78:79]
	s_waitcnt vmcnt(0)
	v_lshlrev_b32_e32 v148, 16, v49
	v_and_b32_e32 v149, 0xffff0000, v49
	v_and_b32_e32 v49, 0xffff0000, v56
	v_lshlrev_b32_e32 v145, 16, v48
	v_and_b32_e32 v146, 0xffff0000, v48
	v_lshlrev_b32_e32 v48, 16, v56
	v_mul_f32_e32 v49, v49, v49
	v_lshlrev_b32_e32 v150, 16, v50
	v_and_b32_e32 v151, 0xffff0000, v50
	v_lshlrev_b32_e32 v50, 16, v57
	v_fmac_f32_e32 v49, v48, v48
	v_lshlrev_b32_e32 v152, 16, v51
	v_and_b32_e32 v153, 0xffff0000, v51
	v_and_b32_e32 v51, 0xffff0000, v57
	v_fmac_f32_e32 v49, v50, v50
	v_lshlrev_b32_e32 v154, 16, v52
	v_and_b32_e32 v155, 0xffff0000, v52
	v_lshlrev_b32_e32 v52, 16, v58
	v_fmac_f32_e32 v49, v51, v51
	v_lshlrev_b32_e32 v156, 16, v53
	v_and_b32_e32 v157, 0xffff0000, v53
	v_and_b32_e32 v53, 0xffff0000, v58
	v_fmac_f32_e32 v49, v52, v52
	v_lshlrev_b32_e32 v158, 16, v54
	v_and_b32_e32 v159, 0xffff0000, v54
	v_lshlrev_b32_e32 v54, 16, v59
	v_fmac_f32_e32 v49, v53, v53
	v_lshlrev_b32_e32 v160, 16, v55
	v_and_b32_e32 v161, 0xffff0000, v55
	v_and_b32_e32 v55, 0xffff0000, v59
	v_fmac_f32_e32 v49, v54, v54
	v_fmac_f32_e32 v49, v55, v55
	ds_bpermute_b32 v48, v63, v49
	v_lshlrev_b32_e32 v162, 16, v86
	v_and_b32_e32 v163, 0xffff0000, v86
	v_lshlrev_b32_e32 v164, 16, v87
	v_and_b32_e32 v165, 0xffff0000, v87
	s_waitcnt lgkmcnt(0)
	v_add_f32_e32 v48, v49, v48
	ds_bpermute_b32 v49, v108, v48
	v_lshlrev_b32_e32 v166, 16, v88
	v_and_b32_e32 v167, 0xffff0000, v88
	v_lshlrev_b32_e32 v168, 16, v89
	v_and_b32_e32 v169, 0xffff0000, v89
	s_waitcnt lgkmcnt(0)
	v_add_f32_e32 v48, v48, v49
	ds_bpermute_b32 v49, v109, v48
	v_lshlrev_b32_e32 v170, 16, v90
	v_and_b32_e32 v171, 0xffff0000, v90
	v_lshlrev_b32_e32 v172, 16, v91
	v_and_b32_e32 v173, 0xffff0000, v91
	s_waitcnt lgkmcnt(0)
	v_add_f32_e32 v48, v48, v49
	ds_bpermute_b32 v49, v110, v48
	v_lshlrev_b32_e32 v174, 16, v92
	v_and_b32_e32 v175, 0xffff0000, v92
	v_lshlrev_b32_e32 v176, 16, v93
	v_and_b32_e32 v177, 0xffff0000, v93
	s_waitcnt lgkmcnt(0)
	v_add_f32_e32 v48, v48, v49
	ds_bpermute_b32 v49, v111, v48
	v_mul_f32_e32 v52, v171, v171
	v_fmac_f32_e32 v52, v170, v170
	v_fmac_f32_e32 v52, v172, v172
	v_fmac_f32_e32 v52, v173, v173
	s_waitcnt lgkmcnt(0)
	v_add_f32_e32 v54, v48, v49
	v_lshl_add_u64 v[48:49], s[20:21], 0, v[64:65]
	flat_load_dwordx4 v[86:89], v[48:49]
	flat_load_dwordx4 v[90:93], v[48:49] offset:16
	flat_load_dwordx4 v[114:117], v[48:49] offset:32
	flat_load_dwordx4 v[118:121], v[48:49] offset:48
	flat_load_dwordx4 v[122:125], v[48:49] offset:64
	flat_load_dwordx4 v[126:129], v[48:49] offset:80
	flat_load_dwordx4 v[130:133], v[48:49] offset:96
	flat_load_dwordx4 v[134:137], v[48:49] offset:112
	v_fmac_f32_e32 v52, v174, v174
	v_fmac_f32_e32 v52, v175, v175
	v_fmac_f32_e32 v52, v176, v176
	v_fmac_f32_e32 v52, v177, v177
	v_fmac_f32_e32 v52, v162, v162
	v_fmac_f32_e32 v52, v163, v163
	v_fmac_f32_e32 v52, v164, v164
	v_fmac_f32_e32 v52, v165, v165
	v_fmac_f32_e32 v52, v166, v166
	v_fmac_f32_e32 v52, v167, v167
	v_fmac_f32_e32 v52, v168, v168
	v_fmac_f32_e32 v52, v169, v169
	v_fmac_f32_e32 v52, v145, v145
	v_fmac_f32_e32 v52, v146, v146
	v_fmac_f32_e32 v52, v148, v148
	v_fmac_f32_e32 v52, v149, v149
	v_fmac_f32_e32 v52, v150, v150
	v_fmac_f32_e32 v52, v151, v151
	v_fmac_f32_e32 v52, v152, v152
	v_fmac_f32_e32 v52, v153, v153
	v_fmac_f32_e32 v52, v154, v154
	v_fmac_f32_e32 v52, v155, v155
	v_lshlrev_b32_e32 v99, 16, v41
	v_and_b32_e32 v103, 0xffff0000, v41
	v_fmac_f32_e32 v52, v156, v156
	v_lshlrev_b32_e32 v98, 16, v37
	v_and_b32_e32 v102, 0xffff0000, v37
	v_mov_b32_e32 v50, v103
	v_mov_b32_e32 v51, v99
	v_and_b32_e32 v105, 0xffff0000, v40
	v_and_b32_e32 v104, 0xffff0000, v36
	v_fmac_f32_e32 v52, v157, v157
	v_mov_b32_e32 v48, v102
	v_mov_b32_e32 v49, v98
	v_pk_mul_f32 v[50:51], v[50:51], v[50:51]
	v_lshlrev_b32_e32 v97, 16, v40
	v_lshlrev_b32_e32 v96, 16, v36
	v_pk_mul_f32 v[36:37], v[104:105], v[104:105]
	v_lshlrev_b32_e32 v95, 16, v39
	v_lshlrev_b32_e32 v94, 16, v35
	v_fmac_f32_e32 v52, v158, v158
	v_pk_fma_f32 v[48:49], v[48:49], v[48:49], v[50:51]
	v_pk_mul_f32 v[50:51], v[96:97], v[96:97]
	v_add_f32_e32 v40, v36, v37
	v_pk_mul_f32 v[36:37], v[94:95], v[94:95]
	v_and_b32_e32 v107, 0xffff0000, v39
	v_and_b32_e32 v106, 0xffff0000, v35
	v_fmac_f32_e32 v52, v159, v159
	v_add_f32_e32 v41, v50, v51
	v_add_f32_e32 v50, v36, v37
	v_pk_mul_f32 v[36:37], v[106:107], v[106:107]
	v_lshlrev_b32_e32 v139, 16, v38
	v_lshlrev_b32_e32 v138, 16, v34
	v_fmac_f32_e32 v52, v160, v160
	v_add_f32_e32 v39, v36, v37
	v_pk_mul_f32 v[36:37], v[138:139], v[138:139]
	v_fmac_f32_e32 v52, v161, v161
	v_add_f32_e32 v35, v36, v37
	v_and_b32_e32 v141, 0xffff0000, v38
	v_and_b32_e32 v140, 0xffff0000, v34
	v_add_f32_e32 v36, v35, v52
	v_pk_mul_f32 v[34:35], v[140:141], v[140:141]
	ds_bpermute_b32 v55, v112, v54
	v_add_f32_e32 v34, v34, v35
	v_add_f32_e32 v34, v34, v36
	v_add_f32_e32 v34, v50, v34
	v_add_f32_e32 v34, v39, v34
	v_add_f32_e32 v34, v41, v34
	v_add_f32_e32 v34, v40, v34
	v_add_f32_e32 v34, v49, v34
	v_add_f32_e32 v34, v48, v34
	ds_bpermute_b32 v35, v63, v34
	s_waitcnt lgkmcnt(0)
	v_add_f32_e32 v36, v54, v55
	v_fmamk_f32 v36, v36, 0x3b000000, v113
	v_rsq_f32_e32 v144, v36
	global_load_dwordx4 v[58:61], v[44:45], off offset:2112
	global_load_dwordx4 v[50:53], v[46:47], off offset:16
	v_add_f32_e32 v38, v34, v35
	ds_bpermute_b32 v39, v108, v38
	global_load_dwordx4 v[54:57], v[82:83], off
	global_load_dwordx4 v[46:49], v[82:83], off offset:64
	global_load_dwordx4 v[34:37], v[42:43], off offset:48
	s_waitcnt lgkmcnt(0)
	v_add_f32_e32 v38, v38, v39
	v_mul_f32_e32 v38, v144, v38
	v_mul_f32_e32 v38, v144, v38
	v_fmamk_f32 v38, v38, 0x3baaaaab, v113
	v_rsq_f32_e32 v178, v38
	global_load_dwordx4 v[38:41], v[42:43], off offset:32
	s_nop 0
	global_load_dwordx4 v[42:45], v[42:43], off offset:16
	v_mul_f32_e32 v144, v144, v178
	v_mul_f32_e32 v144, 0x3dd53b95, v144
	s_waitcnt vmcnt(0)
	v_mul_f32_e32 v86, v86, v144
	v_mul_f32_e32 v87, v87, v144
	v_mul_f32_e32 v88, v88, v144
	v_mul_f32_e32 v89, v89, v144
	v_mul_f32_e32 v86, v86, v170
	v_mul_f32_e32 v87, v87, v171
	v_mul_f32_e32 v88, v88, v172
	v_mul_f32_e32 v89, v89, v173
	v_mul_f32_e32 v90, v90, v144
	v_mul_f32_e32 v91, v91, v144
	v_mul_f32_e32 v92, v92, v144
	v_mul_f32_e32 v93, v93, v144
	v_mul_f32_e32 v90, v90, v174
	v_mul_f32_e32 v91, v91, v175
	v_mul_f32_e32 v92, v92, v176
	v_mul_f32_e32 v93, v93, v177
	v_mul_f32_e32 v114, v114, v144
	v_mul_f32_e32 v115, v115, v144
	v_mul_f32_e32 v116, v116, v144
	v_mul_f32_e32 v117, v117, v144
	v_mul_f32_e32 v118, v118, v144
	v_mul_f32_e32 v119, v119, v144
	v_mul_f32_e32 v120, v120, v144
	v_mul_f32_e32 v121, v121, v144
	v_cvt_pk_bf16_f32 v86, v86, v87
	v_cvt_pk_bf16_f32 v87, v88, v89
	v_cvt_pk_bf16_f32 v88, v90, v91
	v_cvt_pk_bf16_f32 v89, v92, v93
	v_mul_f32_e32 v114, v114, v162
	v_mul_f32_e32 v115, v115, v163
	v_mul_f32_e32 v116, v116, v164
	v_mul_f32_e32 v117, v117, v165
	v_mul_f32_e32 v118, v118, v166
	v_mul_f32_e32 v119, v119, v167
	v_mul_f32_e32 v120, v120, v168
	v_mul_f32_e32 v121, v121, v169
	v_mul_f32_e32 v122, v122, v144
	v_mul_f32_e32 v123, v123, v144
	v_mul_f32_e32 v124, v124, v144
	v_mul_f32_e32 v125, v125, v144
	v_mul_f32_e32 v126, v126, v144
	v_mul_f32_e32 v127, v127, v144
	v_mul_f32_e32 v128, v128, v144
	v_mul_f32_e32 v129, v129, v144
	global_store_dwordx4 v[84:85], v[86:89], off
	v_mul_f32_e32 v122, v122, v145
	v_mul_f32_e32 v123, v123, v146
	v_cvt_pk_bf16_f32 v86, v114, v115
	v_cvt_pk_bf16_f32 v87, v116, v117
	v_cvt_pk_bf16_f32 v88, v118, v119
	v_cvt_pk_bf16_f32 v89, v120, v121
	v_mul_f32_e32 v124, v124, v148
	v_mul_f32_e32 v125, v125, v149
	v_mul_f32_e32 v126, v126, v150
	v_mul_f32_e32 v127, v127, v151
	v_mul_f32_e32 v128, v128, v152
	v_mul_f32_e32 v129, v129, v153
	v_mul_f32_e32 v130, v130, v144
	v_mul_f32_e32 v131, v131, v144
	v_mul_f32_e32 v132, v132, v144
	v_mul_f32_e32 v133, v133, v144
	v_mul_f32_e32 v134, v134, v144
	v_mul_f32_e32 v135, v135, v144
	v_mul_f32_e32 v136, v136, v144
	v_mul_f32_e32 v137, v137, v144
	global_store_dwordx4 v[84:85], v[86:89], off offset:16
	v_mul_f32_e32 v130, v130, v154
	v_mul_f32_e32 v131, v131, v155
	v_cvt_pk_bf16_f32 v86, v122, v123
	v_cvt_pk_bf16_f32 v87, v124, v125
	v_cvt_pk_bf16_f32 v88, v126, v127
	v_cvt_pk_bf16_f32 v89, v128, v129
	v_mul_f32_e32 v132, v132, v156
	v_mul_f32_e32 v133, v133, v157
	v_mul_f32_e32 v134, v134, v158
	v_mul_f32_e32 v135, v135, v159
	v_mul_f32_e32 v136, v136, v160
	v_mul_f32_e32 v137, v137, v161
	global_store_dwordx4 v[84:85], v[86:89], off offset:32
	v_pk_mul_f32 v[92:93], v[144:145], v[138:139] op_sel_hi:[0,1]
	v_mov_b32_e32 v90, v10
	v_cvt_pk_bf16_f32 v86, v130, v131
	v_cvt_pk_bf16_f32 v87, v132, v133
	v_cvt_pk_bf16_f32 v88, v134, v135
	v_cvt_pk_bf16_f32 v89, v136, v137
	global_store_dwordx4 v[84:85], v[86:89], off offset:48
	flat_load_dwordx4 v[114:117], v[142:143] offset:512
	flat_load_dwordx4 v[118:121], v[142:143] offset:640
	flat_load_dwordx4 v[122:125], v[142:143] offset:528
	flat_load_dwordx4 v[126:129], v[142:143] offset:656
	v_mov_b32_e32 v91, v14
	v_pk_mul_f32 v[94:95], v[144:145], v[94:95] op_sel_hi:[0,1]
	v_mov_b32_e32 v88, v12
	v_mov_b32_e32 v89, v16
	v_pk_mul_f32 v[106:107], v[144:145], v[106:107] op_sel_hi:[0,1]
	v_pk_mul_f32 v[96:97], v[144:145], v[96:97] op_sel_hi:[0,1]
	v_mov_b32_e32 v86, v2
	v_mov_b32_e32 v87, v6
	v_pk_mul_f32 v[104:105], v[144:145], v[104:105] op_sel_hi:[0,1]
	v_pk_mul_f32 v[98:99], v[144:145], v[98:99] op_sel_hi:[0,1]
	v_mov_b32_e32 v84, v4
	v_mov_b32_e32 v85, v8
	v_pk_mul_f32 v[102:103], v[144:145], v[102:103] op_sel_hi:[0,1]
	s_waitcnt vmcnt(0) lgkmcnt(0)
	v_mov_b32_e32 v130, v114
	v_mov_b32_e32 v131, v118
	v_pk_mul_f32 v[130:131], v[92:93], v[130:131]
	v_mov_b32_e32 v118, v115
	v_pk_mul_f32 v[92:93], v[90:91], v[130:131]
	s_nop 0
	v_sub_f32_e32 v132, v92, v93
	v_mov_b32_e32 v92, v14
	v_mov_b32_e32 v93, v10
	v_pk_mul_f32 v[130:131], v[92:93], v[130:131]
	v_mov_b32_e32 v14, v11
	v_add_f32_e32 v133, v130, v131
	v_pk_mul_f32 v[130:131], v[144:145], v[140:141] op_sel_hi:[0,1]
	v_pk_mul_f32 v[114:115], v[130:131], v[118:119]
	v_mov_b32_e32 v10, v15
	v_pk_mul_f32 v[118:119], v[14:15], v[114:115]
	v_pk_mul_f32 v[114:115], v[10:11], v[114:115]
	v_sub_f32_e32 v118, v118, v119
	v_add_f32_e32 v119, v114, v115
	v_mov_b32_e32 v114, v116
	v_mov_b32_e32 v115, v120
	v_pk_mul_f32 v[114:115], v[94:95], v[114:115]
	v_mov_b32_e32 v120, v117
	v_pk_mul_f32 v[94:95], v[88:89], v[114:115]
	v_pk_mul_f32 v[106:107], v[106:107], v[120:121]
	v_sub_f32_e32 v116, v94, v95
	v_mov_b32_e32 v94, v16
	v_mov_b32_e32 v95, v12
	v_pk_mul_f32 v[114:115], v[94:95], v[114:115]
	v_mov_b32_e32 v16, v13
	v_mov_b32_e32 v12, v17
	v_add_f32_e32 v130, v114, v115
	v_pk_mul_f32 v[114:115], v[16:17], v[106:107]
	v_pk_mul_f32 v[106:107], v[12:13], v[106:107]
	v_sub_f32_e32 v114, v114, v115
	v_add_f32_e32 v115, v106, v107
	v_mov_b32_e32 v106, v122
	v_mov_b32_e32 v107, v126
	v_pk_mul_f32 v[106:107], v[96:97], v[106:107]
	v_mov_b32_e32 v126, v123
	v_pk_mul_f32 v[96:97], v[86:87], v[106:107]
	v_pk_mul_f32 v[104:105], v[104:105], v[126:127]
	v_sub_f32_e32 v117, v96, v97
	v_mov_b32_e32 v96, v6
	v_mov_b32_e32 v97, v2
	v_pk_mul_f32 v[106:107], v[96:97], v[106:107]
	v_mov_b32_e32 v6, v3
	v_mov_b32_e32 v2, v7
	v_add_f32_e32 v120, v106, v107
	v_pk_mul_f32 v[106:107], v[6:7], v[104:105]
	v_pk_mul_f32 v[104:105], v[2:3], v[104:105]
	v_sub_f32_e32 v106, v106, v107
	v_add_f32_e32 v107, v104, v105
	v_mov_b32_e32 v104, v124
	v_mov_b32_e32 v105, v128
	v_pk_mul_f32 v[104:105], v[98:99], v[104:105]
	v_mov_b32_e32 v128, v125
	v_pk_mul_f32 v[98:99], v[84:85], v[104:105]
	v_pk_mul_f32 v[102:103], v[102:103], v[128:129]
	v_sub_f32_e32 v121, v98, v99
	v_mov_b32_e32 v98, v8
	v_mov_b32_e32 v99, v4
	v_pk_mul_f32 v[104:105], v[98:99], v[104:105]
	v_mov_b32_e32 v8, v5
	v_add_f32_e32 v122, v104, v105
	v_pk_mul_f32 v[104:105], v[8:9], v[102:103]
	v_mov_b32_e32 v4, v9
	v_sub_f32_e32 v105, v104, v105
	v_pk_mul_f32 v[102:103], v[4:5], v[102:103]
	s_nop 0
	v_add_f32_e32 v123, v102, v103
	v_cvt_pk_bf16_f32 v102, v132, v118
	v_cvt_pk_bf16_f32 v103, v116, v114
	v_cvt_pk_bf16_f32 v104, v117, v106
	v_cvt_pk_bf16_f32 v105, v121, v105
	global_store_dwordx4 v[100:101], v[102:105], off
	s_nop 1
	v_cvt_pk_bf16_f32 v102, v133, v119
	v_cvt_pk_bf16_f32 v103, v130, v115
	v_cvt_pk_bf16_f32 v104, v120, v107
	v_cvt_pk_bf16_f32 v105, v122, v123
	global_store_dwordx4 v[100:101], v[102:105], off offset:64
	v_and_b32_e32 v146, 0xffff0000, v54
	v_lshlrev_b32_e32 v148, 16, v54
	v_mul_f32_e32 v185, v146, v146
	v_lshlrev_b32_e32 v145, 16, v55
	v_fmac_f32_e32 v185, v148, v148
	v_and_b32_e32 v144, 0xffff0000, v55
	v_fmac_f32_e32 v185, v145, v145
	v_lshlrev_b32_e32 v152, 16, v56
	v_fmac_f32_e32 v185, v144, v144
	v_and_b32_e32 v151, 0xffff0000, v56
	v_fmac_f32_e32 v185, v152, v152
	v_lshlrev_b32_e32 v150, 16, v57
	v_fmac_f32_e32 v185, v151, v151
	v_and_b32_e32 v149, 0xffff0000, v57
	v_fmac_f32_e32 v185, v150, v150
	v_lshlrev_b32_e32 v139, 16, v50
	v_fmac_f32_e32 v185, v149, v149
	v_and_b32_e32 v158, 0xffff0000, v30
	v_lshlrev_b32_e32 v156, 16, v31
	v_and_b32_e32 v155, 0xffff0000, v31
	v_lshlrev_b32_e32 v154, 16, v32
	v_and_b32_e32 v153, 0xffff0000, v32
	v_and_b32_e32 v106, 0xffff0000, v33
	v_lshlrev_b32_e32 v107, 16, v33
	v_and_b32_e32 v31, 0xffff0000, v58
	v_lshlrev_b32_e32 v33, 16, v59
	v_lshlrev_b32_e32 v32, 16, v58
	v_and_b32_e32 v138, 0xffff0000, v50
	v_fmac_f32_e32 v185, v139, v139
	v_lshlrev_b32_e32 v157, 16, v30
	v_and_b32_e32 v30, 0xffff0000, v26
	v_lshlrev_b32_e32 v101, 16, v27
	v_lshlrev_b32_e32 v100, 16, v26
	v_lshlrev_b32_e32 v103, 16, v28
	v_and_b32_e32 v102, 0xffff0000, v27
	v_lshlrev_b32_e32 v27, 16, v60
	v_lshlrev_b32_e32 v105, 16, v29
	v_and_b32_e32 v104, 0xffff0000, v28
	v_and_b32_e32 v58, 0xffff0000, v60
	v_and_b32_e32 v60, 0xffff0000, v29
	v_lshlrev_b32_e32 v137, 16, v51
	v_lshlrev_b32_e32 v115, 16, v46
	v_and_b32_e32 v114, 0xffff0000, v46
	v_lshlrev_b32_e32 v57, 16, v47
	v_and_b32_e32 v56, 0xffff0000, v47
	v_lshlrev_b32_e32 v47, 16, v40
	v_and_b32_e32 v46, 0xffff0000, v40
	v_and_b32_e32 v28, 0xffff0000, v41
	v_lshlrev_b32_e32 v29, 16, v41
	v_mul_f32_e32 v184, v158, v158
	v_pk_mul_f32 v[40:41], v[106:107], v[106:107]
	v_mul_f32_e32 v106, v31, v31
	v_pk_mul_f32 v[166:167], v[32:33], v[32:33]
	v_fmac_f32_e32 v185, v138, v138
	v_and_b32_e32 v26, 0xffff0000, v59
	v_and_b32_e32 v136, 0xffff0000, v51
	v_lshlrev_b32_e32 v123, 16, v18
	v_and_b32_e32 v122, 0xffff0000, v18
	v_lshlrev_b32_e32 v121, 16, v19
	v_and_b32_e32 v120, 0xffff0000, v19
	v_lshlrev_b32_e32 v127, 16, v20
	v_and_b32_e32 v126, 0xffff0000, v20
	v_lshlrev_b32_e32 v125, 16, v21
	v_and_b32_e32 v124, 0xffff0000, v21
	v_and_b32_e32 v18, 0xffff0000, v34
	v_lshlrev_b32_e32 v19, 16, v34
	v_and_b32_e32 v20, 0xffff0000, v35
	v_lshlrev_b32_e32 v21, 16, v35
	v_lshl_add_u64 v[34:35], s[18:19], 0, v[80:81]
	v_fmac_f32_e32 v184, v157, v157
	v_pk_fma_f32 v[106:107], v[30:31], v[30:31], v[106:107] op_sel_hi:[1,1,0]
	v_pk_fma_f32 v[166:167], v[100:101], v[100:101], v[166:167]
	v_fmac_f32_e32 v185, v137, v137
	v_lshlrev_b32_e32 v143, 16, v52
	v_pk_mul_f32 v[168:169], v[26:27], v[26:27]
	v_mov_b32_e32 v158, v190
	v_mov_b32_e32 v159, v191
	v_mov_b32_e32 v160, v192
	v_mov_b32_e32 v161, v193
	v_mov_b32_e32 v162, v194
	v_mov_b32_e32 v163, v195
	v_mov_b32_e32 v164, v196
	v_mov_b32_e32 v165, v197
	v_fmac_f32_e32 v184, v156, v156
	v_pk_add_f32 v[106:107], v[166:167], v[106:107]
	v_fmac_f32_e32 v185, v136, v136
	v_lshlrev_b32_e32 v59, 16, v61
	v_and_b32_e32 v142, 0xffff0000, v52
	v_pk_fma_f32 v[168:169], v[102:103], v[102:103], v[168:169]
	v_fmac_f32_e32 v184, v155, v155
	v_pk_add_f32 v[106:107], v[166:167], v[106:107] op_sel:[1,0] op_sel_hi:[0,1]
	v_fmac_f32_e32 v185, v143, v143
	v_lshlrev_b32_e32 v141, 16, v53
	v_pk_mul_f32 v[170:171], v[58:59], v[58:59]
	v_fmac_f32_e32 v184, v154, v154
	v_pk_add_f32 v[106:107], v[168:169], v[106:107]
	v_fmac_f32_e32 v185, v142, v142
	v_and_b32_e32 v140, 0xffff0000, v53
	v_pk_fma_f32 v[170:171], v[104:105], v[104:105], v[170:171]
	v_fmac_f32_e32 v184, v153, v153
	v_pk_add_f32 v[106:107], v[168:169], v[106:107] op_sel:[1,0] op_sel_hi:[0,1]
	v_fmac_f32_e32 v185, v141, v141
	v_lshlrev_b32_e32 v131, 16, v22
	v_add_f32_e32 v41, v41, v184
	v_pk_add_f32 v[106:107], v[170:171], v[106:107]
	v_fmac_f32_e32 v185, v140, v140
	v_and_b32_e32 v130, 0xffff0000, v22
	v_add_f32_e32 v153, v40, v41
	v_pk_add_f32 v[40:41], v[170:171], v[106:107] op_sel:[1,0] op_sel_hi:[0,1]
	v_fmac_f32_e32 v185, v131, v131
	v_lshlrev_b32_e32 v129, 16, v23
	ds_bpermute_b32 v41, v63, v153
	v_fmac_f32_e32 v185, v130, v130
	v_and_b32_e32 v128, 0xffff0000, v23
	v_fmac_f32_e32 v185, v129, v129
	v_lshlrev_b32_e32 v135, 16, v24
	v_fmac_f32_e32 v185, v128, v128
	v_and_b32_e32 v134, 0xffff0000, v24
	v_fmac_f32_e32 v185, v135, v135
	v_lshlrev_b32_e32 v133, 16, v25
	v_fmac_f32_e32 v185, v134, v134
	v_and_b32_e32 v132, 0xffff0000, v25
	s_waitcnt lgkmcnt(0)
	v_add_f32_e32 v41, v153, v41
	v_fmac_f32_e32 v185, v133, v133
	ds_bpermute_b32 v106, v108, v41
	v_fmac_f32_e32 v185, v132, v132
	v_fmac_f32_e32 v185, v123, v123
	v_fmac_f32_e32 v185, v122, v122
	v_fmac_f32_e32 v185, v121, v121
	v_fmac_f32_e32 v185, v120, v120
	s_waitcnt lgkmcnt(0)
	v_add_f32_e32 v41, v41, v106
	v_fmac_f32_e32 v185, v127, v127
	ds_bpermute_b32 v106, v109, v41
	v_fmac_f32_e32 v185, v126, v126
	v_fmac_f32_e32 v185, v125, v125
	v_fmac_f32_e32 v185, v124, v124
	v_fmac_f32_e32 v185, v115, v115
	v_fmac_f32_e32 v185, v114, v114
	s_waitcnt lgkmcnt(0)
	v_add_f32_e32 v41, v41, v106
	v_fmac_f32_e32 v185, v57, v57
	v_lshlrev_b32_e32 v119, 16, v48
	ds_bpermute_b32 v106, v110, v41
	v_fmac_f32_e32 v185, v56, v56
	v_and_b32_e32 v118, 0xffff0000, v48
	v_fmac_f32_e32 v185, v119, v119
	v_lshlrev_b32_e32 v117, 16, v49
	v_fmac_f32_e32 v185, v118, v118
	v_and_b32_e32 v116, 0xffff0000, v49
	v_fmac_f32_e32 v185, v117, v117
	v_lshlrev_b32_e32 v51, 16, v42
	v_fmac_f32_e32 v185, v116, v116
	v_and_b32_e32 v50, 0xffff0000, v42
	s_waitcnt lgkmcnt(0)
	v_add_f32_e32 v41, v41, v106
	v_fmac_f32_e32 v185, v51, v51
	v_lshlrev_b32_e32 v49, 16, v43
	ds_bpermute_b32 v106, v111, v41
	v_fmac_f32_e32 v185, v50, v50
	v_and_b32_e32 v48, 0xffff0000, v43
	v_fmac_f32_e32 v185, v49, v49
	v_lshlrev_b32_e32 v55, 16, v44
	v_fmac_f32_e32 v185, v48, v48
	v_and_b32_e32 v54, 0xffff0000, v44
	v_fmac_f32_e32 v185, v55, v55
	v_lshlrev_b32_e32 v53, 16, v45
	v_fmac_f32_e32 v185, v54, v54
	v_and_b32_e32 v52, 0xffff0000, v45
	s_waitcnt lgkmcnt(0)
	v_add_f32_e32 v41, v41, v106
	v_fmac_f32_e32 v185, v53, v53
	v_lshlrev_b32_e32 v45, 16, v38
	ds_bpermute_b32 v106, v112, v41
	v_fmac_f32_e32 v185, v52, v52
	v_and_b32_e32 v44, 0xffff0000, v38
	v_fmac_f32_e32 v185, v45, v45
	v_lshlrev_b32_e32 v43, 16, v39
	v_fmac_f32_e32 v185, v44, v44
	v_and_b32_e32 v42, 0xffff0000, v39
	v_fmac_f32_e32 v185, v43, v43
	v_fmac_f32_e32 v185, v42, v42
	s_waitcnt lgkmcnt(0)
	v_add_f32_e32 v41, v41, v106
	v_fmac_f32_e32 v185, v47, v47
	v_pk_mul_f32 v[172:173], v[28:29], v[28:29]
	v_fmamk_f32 v41, v41, 0x3b000000, v113
	v_fmac_f32_e32 v185, v46, v46
	v_rsq_f32_e32 v153, v41
	v_add_f32_e32 v41, v173, v185
	v_pk_mul_f32 v[174:175], v[18:19], v[18:19]
	v_add_f32_e32 v41, v172, v41
	v_add_f32_e32 v41, v175, v41
	v_pk_mul_f32 v[176:177], v[20:21], v[20:21]
	v_add_f32_e32 v41, v174, v41
	v_and_b32_e32 v22, 0xffff0000, v36
	v_lshlrev_b32_e32 v23, 16, v36
	v_add_f32_e32 v41, v177, v41
	v_pk_mul_f32 v[178:179], v[22:23], v[22:23]
	v_add_f32_e32 v41, v176, v41
	v_and_b32_e32 v24, 0xffff0000, v37
	v_lshlrev_b32_e32 v25, 16, v37
	v_add_f32_e32 v41, v179, v41
	v_and_b32_e32 v61, 0xffff0000, v61
	v_pk_mul_f32 v[180:181], v[24:25], v[24:25]
	v_add_f32_e32 v41, v178, v41
	v_mul_f32_e32 v182, v61, v61
	v_add_f32_e32 v41, v181, v41
	v_pk_fma_f32 v[182:183], v[60:61], v[60:61], v[182:183] op_sel_hi:[1,1,0]
	v_add_f32_e32 v41, v180, v41
	v_cndmask_b32_e64 v183, 0, v41, s[0:1]
	ds_bpermute_b32 v106, v63, v183
	s_waitcnt vmcnt(0)
	v_cndmask_b32_e64 v155, v159, 1.0, s[4:5]
	v_cndmask_b32_e64 v156, v158, 1.0, s[4:5]
	v_cndmask_b32_e64 v159, v163, 1.0, s[4:5]
	v_cndmask_b32_e64 v154, v160, 1.0, s[4:5]
	s_waitcnt lgkmcnt(0)
	v_mov_b32_e32 v41, v106
	v_pk_add_f32 v[40:41], v[182:183], v[40:41]
	ds_bpermute_b32 v106, v63, v40
	ds_bpermute_b32 v107, v108, v41
	v_cndmask_b32_e64 v157, v165, 1.0, s[4:5]
	v_cndmask_b32_e64 v158, v164, 1.0, s[4:5]
	v_cndmask_b32_e64 v160, v162, 1.0, s[4:5]
	v_lshl_add_u64 v[36:37], s[18:19], 0, v[78:79]
	s_waitcnt lgkmcnt(0)
	v_pk_add_f32 v[40:41], v[40:41], v[106:107]
	ds_bpermute_b32 v106, v108, v40
	v_mul_f32_e32 v41, v41, v153
	v_cndmask_b32_e64 v107, v161, 1.0, s[4:5]
	v_lshl_add_u64 v[38:39], s[96:97], 0, v[76:77]
	s_add_i32 s31, s31, s46
	s_waitcnt lgkmcnt(0)
	v_add_f32_e32 v40, v40, v106
	v_fmac_f32_e32 v40, v153, v41
	v_fmamk_f32 v40, v40, 0x3baaaaab, v113
	v_rsq_f32_e32 v40, v40
	s_add_i32 s26, s26, s27
	v_add_co_u32_e32 v38, vcc, s28, v38
	v_mul_f32_e32 v41, v153, v40
	v_cndmask_b32_e64 v41, v153, v41, s[0:1]
	v_mul_f32_e32 v106, v156, v41
	v_mul_f32_e32 v156, v159, v41
	v_mul_f32_e32 v153, v160, v41
	v_mul_f32_e32 v155, v155, v41
	v_mul_f32_e32 v154, v154, v41
	v_mul_f32_e32 v158, v158, v41
	v_mul_f32_e32 v107, v107, v41
	v_mul_f32_e32 v157, v157, v41
	v_mul_f32_e32 v151, v156, v151
	v_mul_f32_e32 v106, v106, v148
	v_mul_f32_e32 v152, v153, v152
	v_mul_f32_e32 v146, v155, v146
	v_mul_f32_e32 v145, v154, v145
	v_mul_f32_e32 v153, v158, v150
	v_mul_f32_e32 v107, v107, v144
	v_mul_f32_e32 v144, v157, v149
	v_cvt_pk_bf16_f32 v148, v106, v146
	v_cvt_pk_bf16_f32 v149, v145, v107
	v_cvt_pk_bf16_f32 v150, v152, v151
	v_cvt_pk_bf16_f32 v151, v153, v144
	global_store_dwordx4 v[82:83], v[148:151], off
	s_nop 1
	v_mov_b32_e32 v148, v198
	v_mov_b32_e32 v149, v199
	v_mov_b32_e32 v150, v200
	v_mov_b32_e32 v151, v201
	s_nop 0
	v_mov_b32_e32 v152, v202
	v_mov_b32_e32 v153, v203
	v_mov_b32_e32 v154, v204
	v_mov_b32_e32 v155, v205
	v_lshl_add_u64 v[66:67], v[66:67], 0, s[6:7]
	v_lshl_add_u64 v[68:69], v[68:69], 0, s[8:9]
	v_lshl_add_u64 v[70:71], v[70:71], 0, s[8:9]
	v_lshl_add_u64 v[72:73], v[72:73], 0, s[10:11]
	v_lshl_add_u64 v[74:75], v[74:75], 0, s[10:11]
	v_lshl_add_u64 v[76:77], v[76:77], 0, s[10:11]
	v_addc_co_u32_e32 v39, vcc, 0, v39, vcc
	s_cmp_lt_i32 s31, 0x8000
	s_waitcnt lgkmcnt(0)
	v_cndmask_b32_e64 v144, v149, 1.0, s[4:5]
	v_cndmask_b32_e64 v145, v148, 1.0, s[4:5]
	v_cndmask_b32_e64 v106, v151, 1.0, s[4:5]
	v_cndmask_b32_e64 v107, v150, 1.0, s[4:5]
	v_cndmask_b32_e64 v146, v155, 1.0, s[4:5]
	v_cndmask_b32_e64 v148, v154, 1.0, s[4:5]
	v_cndmask_b32_e64 v149, v153, 1.0, s[4:5]
	v_cndmask_b32_e64 v150, v152, 1.0, s[4:5]
	v_mul_f32_e32 v145, v145, v41
	v_mul_f32_e32 v144, v144, v41
	v_mul_f32_e32 v150, v41, v150
	v_mul_f32_e32 v149, v41, v149
	v_mul_f32_e32 v107, v107, v41
	v_mul_f32_e32 v148, v41, v148
	v_mul_f32_e32 v106, v106, v41
	v_mul_f32_e32 v146, v41, v146
	v_mul_f32_e32 v139, v145, v139
	v_mul_f32_e32 v138, v144, v138
	v_mul_f32_e32 v143, v150, v143
	v_mul_f32_e32 v142, v149, v142
	v_mul_f32_e32 v107, v107, v137
	v_mul_f32_e32 v141, v148, v141
	v_mul_f32_e32 v106, v106, v136
	v_mul_f32_e32 v140, v146, v140
	v_cvt_pk_bf16_f32 v136, v139, v138
	v_cvt_pk_bf16_f32 v137, v107, v106
	v_cvt_pk_bf16_f32 v138, v143, v142
	v_cvt_pk_bf16_f32 v139, v141, v140
	global_store_dwordx4 v[82:83], v[136:139], off offset:16
	s_nop 1
	v_mov_b32_e32 v136, v206
	v_mov_b32_e32 v137, v207
	v_mov_b32_e32 v138, v208
	v_mov_b32_e32 v139, v209
	s_nop 0
	v_mov_b32_e32 v140, v210
	v_mov_b32_e32 v141, v211
	v_mov_b32_e32 v142, v212
	v_mov_b32_e32 v143, v213
	s_waitcnt lgkmcnt(0)
	v_cndmask_b32_e64 v137, v137, 1.0, s[4:5]
	v_cndmask_b32_e64 v136, v136, 1.0, s[4:5]
	v_cndmask_b32_e64 v106, v139, 1.0, s[4:5]
	v_cndmask_b32_e64 v107, v138, 1.0, s[4:5]
	v_cndmask_b32_e64 v138, v143, 1.0, s[4:5]
	v_cndmask_b32_e64 v139, v142, 1.0, s[4:5]
	v_cndmask_b32_e64 v141, v141, 1.0, s[4:5]
	v_cndmask_b32_e64 v140, v140, 1.0, s[4:5]
	v_mul_f32_e32 v136, v41, v136
	v_mul_f32_e32 v137, v41, v137
	v_mul_f32_e32 v140, v41, v140
	v_mul_f32_e32 v141, v41, v141
	v_mul_f32_e32 v107, v41, v107
	v_mul_f32_e32 v139, v41, v139
	v_mul_f32_e32 v106, v41, v106
	v_mul_f32_e32 v138, v41, v138
	v_mul_f32_e32 v131, v136, v131
	v_mul_f32_e32 v130, v137, v130
	v_mul_f32_e32 v135, v140, v135
	v_mul_f32_e32 v134, v141, v134
	v_mul_f32_e32 v107, v107, v129
	v_mul_f32_e32 v133, v139, v133
	v_mul_f32_e32 v106, v106, v128
	v_mul_f32_e32 v132, v138, v132
	v_cvt_pk_bf16_f32 v128, v131, v130
	v_cvt_pk_bf16_f32 v129, v107, v106
	v_cvt_pk_bf16_f32 v130, v135, v134
	v_cvt_pk_bf16_f32 v131, v133, v132
	global_store_dwordx4 v[82:83], v[128:131], off offset:32
	s_nop 1
	v_mov_b32_e32 v128, v214
	v_mov_b32_e32 v129, v215
	v_mov_b32_e32 v130, v216
	v_mov_b32_e32 v131, v217
	s_nop 0
	v_mov_b32_e32 v132, v218
	v_mov_b32_e32 v133, v219
	v_mov_b32_e32 v134, v220
	v_mov_b32_e32 v135, v221
	s_waitcnt lgkmcnt(0)
	v_cndmask_b32_e64 v129, v129, 1.0, s[4:5]
	v_cndmask_b32_e64 v128, v128, 1.0, s[4:5]
	v_cndmask_b32_e64 v106, v131, 1.0, s[4:5]
	v_cndmask_b32_e64 v107, v130, 1.0, s[4:5]
	v_cndmask_b32_e64 v130, v135, 1.0, s[4:5]
	v_cndmask_b32_e64 v131, v134, 1.0, s[4:5]
	v_cndmask_b32_e64 v133, v133, 1.0, s[4:5]
	v_cndmask_b32_e64 v132, v132, 1.0, s[4:5]
	v_mul_f32_e32 v128, v41, v128
	v_mul_f32_e32 v129, v41, v129
	v_mul_f32_e32 v132, v41, v132
	v_mul_f32_e32 v133, v41, v133
	v_mul_f32_e32 v107, v41, v107
	v_mul_f32_e32 v131, v41, v131
	v_mul_f32_e32 v106, v41, v106
	v_mul_f32_e32 v130, v41, v130
	v_mul_f32_e32 v123, v128, v123
	v_mul_f32_e32 v122, v129, v122
	v_mul_f32_e32 v127, v132, v127
	v_mul_f32_e32 v126, v133, v126
	v_mul_f32_e32 v107, v107, v121
	v_mul_f32_e32 v125, v131, v125
	v_mul_f32_e32 v106, v106, v120
	v_mul_f32_e32 v124, v130, v124
	v_cvt_pk_bf16_f32 v120, v123, v122
	v_cvt_pk_bf16_f32 v121, v107, v106
	v_cvt_pk_bf16_f32 v122, v127, v126
	v_cvt_pk_bf16_f32 v123, v125, v124
	global_store_dwordx4 v[82:83], v[120:123], off offset:48
	s_nop 1
	v_mov_b32_e32 v120, v222
	v_mov_b32_e32 v121, v223
	v_mov_b32_e32 v122, v224
	v_mov_b32_e32 v123, v225
	s_nop 0
	v_mov_b32_e32 v124, v226
	v_mov_b32_e32 v125, v227
	v_mov_b32_e32 v126, v228
	v_mov_b32_e32 v127, v229
	s_waitcnt lgkmcnt(0)
	v_cndmask_b32_e64 v121, v121, 1.0, s[4:5]
	v_cndmask_b32_e64 v120, v120, 1.0, s[4:5]
	v_cndmask_b32_e64 v106, v123, 1.0, s[4:5]
	v_cndmask_b32_e64 v107, v122, 1.0, s[4:5]
	v_cndmask_b32_e64 v122, v127, 1.0, s[4:5]
	v_cndmask_b32_e64 v123, v126, 1.0, s[4:5]
	v_cndmask_b32_e64 v125, v125, 1.0, s[4:5]
	v_cndmask_b32_e64 v124, v124, 1.0, s[4:5]
	v_mul_f32_e32 v120, v41, v120
	v_mul_f32_e32 v121, v41, v121
	v_mul_f32_e32 v124, v41, v124
	v_mul_f32_e32 v125, v41, v125
	v_mul_f32_e32 v107, v41, v107
	v_mul_f32_e32 v123, v41, v123
	v_mul_f32_e32 v106, v41, v106
	v_mul_f32_e32 v122, v41, v122
	v_mul_f32_e32 v115, v120, v115
	v_mul_f32_e32 v114, v121, v114
	v_mul_f32_e32 v119, v124, v119
	v_mul_f32_e32 v118, v125, v118
	v_mul_f32_e32 v57, v107, v57
	v_mul_f32_e32 v107, v123, v117
	v_mul_f32_e32 v56, v106, v56
	v_mul_f32_e32 v106, v122, v116
	v_cvt_pk_bf16_f32 v114, v115, v114
	v_cvt_pk_bf16_f32 v115, v57, v56
	v_cvt_pk_bf16_f32 v116, v119, v118
	v_cvt_pk_bf16_f32 v117, v107, v106
	global_store_dwordx4 v[82:83], v[114:117], off offset:64
	s_nop 1
	v_mov_b32_e32 v114, v230
	v_mov_b32_e32 v115, v231
	v_mov_b32_e32 v116, v232
	v_mov_b32_e32 v117, v233
	s_nop 0
	v_mov_b32_e32 v118, v234
	v_mov_b32_e32 v119, v235
	v_mov_b32_e32 v120, v236
	v_mov_b32_e32 v121, v237
	s_waitcnt lgkmcnt(0)
	v_cndmask_b32_e64 v57, v116, 1.0, s[4:5]
	v_cndmask_b32_e64 v106, v115, 1.0, s[4:5]
	v_cndmask_b32_e64 v107, v114, 1.0, s[4:5]
	v_cndmask_b32_e64 v56, v117, 1.0, s[4:5]
	v_cndmask_b32_e64 v114, v121, 1.0, s[4:5]
	v_cndmask_b32_e64 v115, v120, 1.0, s[4:5]
	v_cndmask_b32_e64 v116, v119, 1.0, s[4:5]
	v_cndmask_b32_e64 v117, v118, 1.0, s[4:5]
	v_mul_f32_e32 v107, v41, v107
	v_mul_f32_e32 v106, v41, v106
	v_mul_f32_e32 v57, v41, v57
	v_mul_f32_e32 v117, v41, v117
	v_mul_f32_e32 v116, v41, v116
	v_mul_f32_e32 v115, v41, v115
	v_mul_f32_e32 v56, v41, v56
	v_mul_f32_e32 v114, v41, v114
	v_mul_f32_e32 v51, v107, v51
	v_mul_f32_e32 v50, v106, v50
	v_mul_f32_e32 v49, v57, v49
	v_mul_f32_e32 v55, v117, v55
	v_mul_f32_e32 v54, v116, v54
	v_mul_f32_e32 v53, v115, v53
	v_mul_f32_e32 v56, v56, v48
	v_mul_f32_e32 v52, v114, v52
	v_cvt_pk_bf16_f32 v48, v51, v50
	v_cvt_pk_bf16_f32 v49, v49, v56
	v_cvt_pk_bf16_f32 v50, v55, v54
	v_cvt_pk_bf16_f32 v51, v53, v52
	global_store_dwordx4 v[82:83], v[48:51], off offset:80
	s_nop 1
	v_mov_b32_e32 v48, v238
	v_mov_b32_e32 v49, v239
	v_mov_b32_e32 v50, v240
	v_mov_b32_e32 v51, v241
	s_nop 0
	v_mov_b32_e32 v52, v242
	v_mov_b32_e32 v53, v243
	v_mov_b32_e32 v54, v244
	v_mov_b32_e32 v55, v245
	s_waitcnt lgkmcnt(0)
	v_cndmask_b32_e64 v50, v50, 1.0, s[4:5]
	v_cndmask_b32_e64 v49, v49, 1.0, s[4:5]
	v_cndmask_b32_e64 v48, v48, 1.0, s[4:5]
	v_cndmask_b32_e64 v51, v51, 1.0, s[4:5]
	v_cndmask_b32_e64 v55, v55, 1.0, s[4:5]
	v_cndmask_b32_e64 v54, v54, 1.0, s[4:5]
	v_cndmask_b32_e64 v53, v53, 1.0, s[4:5]
	v_cndmask_b32_e64 v52, v52, 1.0, s[4:5]
	v_mul_f32_e32 v48, v41, v48
	v_mul_f32_e32 v49, v41, v49
	v_mul_f32_e32 v50, v41, v50
	v_mul_f32_e32 v52, v41, v52
	v_mul_f32_e32 v53, v41, v53
	v_mul_f32_e32 v54, v41, v54
	v_mul_f32_e32 v51, v41, v51
	v_mul_f32_e32 v55, v41, v55
	v_mul_f32_e32 v45, v48, v45
	v_mul_f32_e32 v44, v49, v44
	v_mul_f32_e32 v43, v50, v43
	v_mul_f32_e32 v47, v52, v47
	v_mul_f32_e32 v46, v53, v46
	v_mul_f32_e32 v29, v54, v29
	v_mul_f32_e32 v48, v51, v42
	v_mul_f32_e32 v28, v55, v28
	v_cvt_pk_bf16_f32 v42, v45, v44
	v_cvt_pk_bf16_f32 v43, v43, v48
	v_cvt_pk_bf16_f32 v44, v47, v46
	v_cvt_pk_bf16_f32 v45, v29, v28
	global_store_dwordx4 v[82:83], v[42:45], off offset:96
	s_nop 1
	v_mov_b32_e32 v42, v246
	v_mov_b32_e32 v43, v247
	v_mov_b32_e32 v44, v248
	v_mov_b32_e32 v45, v249
	s_nop 0
	v_mov_b32_e32 v46, v250
	v_mov_b32_e32 v47, v251
	v_mov_b32_e32 v48, v252
	v_mov_b32_e32 v49, v253
	s_waitcnt lgkmcnt(0)
	v_cndmask_b32_e64 v28, v45, 1.0, s[4:5]
	v_cndmask_b32_e64 v29, v44, 1.0, s[4:5]
	v_cndmask_b32_e64 v34, v43, 1.0, s[4:5]
	v_cndmask_b32_e64 v35, v42, 1.0, s[4:5]
	v_cndmask_b32_e64 v42, v49, 1.0, s[4:5]
	v_cndmask_b32_e64 v43, v48, 1.0, s[4:5]
	v_cndmask_b32_e64 v44, v47, 1.0, s[4:5]
	v_cndmask_b32_e64 v45, v46, 1.0, s[4:5]
	v_mul_f32_e32 v35, v41, v35
	v_mul_f32_e32 v34, v41, v34
	v_mul_f32_e32 v29, v41, v29
	v_mul_f32_e32 v28, v41, v28
	v_mul_f32_e32 v45, v41, v45
	v_mul_f32_e32 v44, v41, v44
	v_mul_f32_e32 v43, v41, v43
	v_mul_f32_e32 v41, v41, v42
	v_mul_f32_e32 v19, v35, v19
	v_mul_f32_e32 v18, v34, v18
	v_mul_f32_e32 v21, v29, v21
	v_mul_f32_e32 v20, v28, v20
	v_mul_f32_e32 v23, v45, v23
	v_mul_f32_e32 v22, v44, v22
	v_mul_f32_e32 v25, v43, v25
	v_mul_f32_e32 v24, v41, v24
	v_cvt_pk_bf16_f32 v18, v19, v18
	v_cvt_pk_bf16_f32 v19, v21, v20
	v_cvt_pk_bf16_f32 v20, v23, v22
	v_cvt_pk_bf16_f32 v21, v25, v24
	global_store_dwordx4 v[82:83], v[18:21], off offset:112
	flat_load_dwordx4 v[18:21], v[36:37] offset:512
	s_nop 0
	flat_load_dwordx4 v[22:25], v[36:37] offset:640
	flat_load_dwordx4 v[42:45], v[36:37] offset:528
	s_nop 0
	flat_load_dwordx4 v[34:37], v[36:37] offset:656
	v_mov_b32_e32 v28, v100
	v_mov_b32_e32 v29, v32
	v_mov_b32_e32 v32, v101
	v_mov_b32_e32 v46, v102
	v_mov_b32_e32 v47, v26
	v_mov_b32_e32 v26, v103
	v_mov_b32_e32 v48, v104
	v_mov_b32_e32 v49, v58
	v_mov_b32_e32 v58, v105
	v_pk_mul_f32 v[28:29], v[40:41], v[28:29] op_sel_hi:[0,1]
	v_pk_mul_f32 v[30:31], v[40:41], v[30:31] op_sel_hi:[0,1]
	v_pk_mul_f32 v[32:33], v[40:41], v[32:33] op_sel_hi:[0,1]
	v_pk_mul_f32 v[46:47], v[40:41], v[46:47] op_sel_hi:[0,1]
	v_pk_mul_f32 v[26:27], v[40:41], v[26:27] op_sel_hi:[0,1]
	v_pk_mul_f32 v[48:49], v[40:41], v[48:49] op_sel_hi:[0,1]
	v_pk_mul_f32 v[50:51], v[40:41], v[58:59] op_sel_hi:[0,1]
	v_pk_mul_f32 v[40:41], v[40:41], v[60:61] op_sel_hi:[0,1]
	s_waitcnt vmcnt(0) lgkmcnt(0)
	v_mov_b32_e32 v52, v18
	v_mov_b32_e32 v53, v22
	v_mov_b32_e32 v22, v19
	v_mov_b32_e32 v18, v20
	v_mov_b32_e32 v19, v24
	v_mov_b32_e32 v24, v21
	v_mov_b32_e32 v20, v42
	v_mov_b32_e32 v21, v34
	v_mov_b32_e32 v34, v43
	v_mov_b32_e32 v42, v44
	v_mov_b32_e32 v43, v36
	v_mov_b32_e32 v36, v45
	v_pk_mul_f32 v[28:29], v[28:29], v[52:53]
	v_pk_mul_f32 v[22:23], v[30:31], v[22:23]
	v_pk_mul_f32 v[18:19], v[32:33], v[18:19]
	v_pk_mul_f32 v[24:25], v[46:47], v[24:25]
	v_pk_mul_f32 v[20:21], v[26:27], v[20:21]
	v_pk_mul_f32 v[26:27], v[48:49], v[34:35]
	v_pk_mul_f32 v[30:31], v[50:51], v[42:43]
	v_pk_mul_f32 v[32:33], v[40:41], v[36:37]
	v_pk_mul_f32 v[34:35], v[90:91], v[28:29]
	v_pk_mul_f32 v[14:15], v[14:15], v[22:23]
	v_pk_mul_f32 v[10:11], v[10:11], v[22:23]
	v_pk_mul_f32 v[22:23], v[88:89], v[18:19]
	v_pk_mul_f32 v[18:19], v[94:95], v[18:19]
	v_pk_mul_f32 v[16:17], v[16:17], v[24:25]
	v_pk_mul_f32 v[12:13], v[12:13], v[24:25]
	v_pk_mul_f32 v[24:25], v[86:87], v[20:21]
	v_pk_mul_f32 v[6:7], v[6:7], v[26:27]
	v_pk_mul_f32 v[2:3], v[2:3], v[26:27]
	v_pk_mul_f32 v[26:27], v[84:85], v[30:31]
	v_pk_mul_f32 v[8:9], v[8:9], v[32:33]
	v_pk_mul_f32 v[4:5], v[4:5], v[32:33]
	v_pk_mul_f32 v[28:29], v[92:93], v[28:29]
	v_pk_mul_f32 v[20:21], v[96:97], v[20:21]
	v_pk_mul_f32 v[30:31], v[98:99], v[30:31]
	v_sub_f32_e32 v32, v34, v35
	v_sub_f32_e32 v14, v14, v15
	v_add_f32_e32 v10, v10, v11
	v_sub_f32_e32 v11, v22, v23
	v_add_f32_e32 v15, v18, v19
	v_sub_f32_e32 v16, v16, v17
	v_add_f32_e32 v12, v12, v13
	v_sub_f32_e32 v13, v24, v25
	v_sub_f32_e32 v6, v6, v7
	v_add_f32_e32 v7, v2, v3
	v_sub_f32_e32 v18, v26, v27
	v_sub_f32_e32 v8, v8, v9
	v_add_f32_e32 v9, v4, v5
	v_cvt_pk_bf16_f32 v2, v32, v14
	v_cvt_pk_bf16_f32 v3, v11, v16
	v_cvt_pk_bf16_f32 v4, v13, v6
	v_cvt_pk_bf16_f32 v5, v18, v8
	v_add_f32_e32 v28, v28, v29
	v_add_f32_e32 v17, v20, v21
	v_add_f32_e32 v19, v30, v31
	global_store_dwordx4 v[38:39], v[2:5], off
	s_nop 1
	v_cvt_pk_bf16_f32 v2, v28, v10
	v_cvt_pk_bf16_f32 v3, v15, v12
	v_cvt_pk_bf16_f32 v4, v17, v7
	v_cvt_pk_bf16_f32 v5, v19, v9
	global_store_dwordx4 v[38:39], v[2:5], off offset:64
	s_cbranch_scc1 .LBB0_275
